# P4 dynamic queue path: ticket broadcast through ds_write_b32/ds_read_b32 instead of flat store/load to the LDS slot
# speedup vs baseline: 1.0059x; 1.0014x over previous
.LBB0_433:
	s_or_b64 exec, exec, s[4:5]
	s_waitcnt vmcnt(0)
	v_readfirstlane_b32 s4, v2
	s_cmp_lg_u32 s83, -1
	s_cselect_b32 s5, s79, 0
	v_add_u32_e32 v0, s4, v0
	s_cselect_b32 s4, s83, 0
	v_mov_b32_e32 v2, s4
	v_mov_b32_e32 v3, s5
	ds_write_b32 v2, v0
	s_waitcnt lgkmcnt(0)
.LBB0_434:
	s_or_b64 exec, exec, s[2:3]
	s_cmp_lg_u32 s83, -1
	s_cselect_b32 s2, s83, 0
	s_cselect_b32 s3, s79, 0
	v_mov_b32_e32 v2, s2
	v_mov_b32_e32 v3, s3
	s_waitcnt lgkmcnt(0)
	s_barrier
	ds_read_b32 v0, v2
	s_waitcnt lgkmcnt(0)
	s_mov_b64 s[2:3], -1
	s_waitcnt lgkmcnt(0)
	v_readfirstlane_b32 s28, v0
	s_cmp_eq_u32 s101, 0
	s_cbranch_scc1 .Lq4_have_u
	s_addk_i32 s28, 0x500
	s_cmp_lt_u32 s28, 0x510
	s_cbranch_scc0 .Lq4_have_u
	s_sub_i32 s28, s28, 0x400
